# speedup vs baseline: 1.0303x; 1.0070x over previous
; __device__ __forceinline__ void norm_phase(ArgP a, LAS unsigned char* lds, int l, bool final_, const int tid, const int bid) {
;     ...
;         for (int col = tid; col < DM; col += NTHR) {
;             float sh = a->b_ada[(size_t)l * NP + col], sc = a->b_ada[(size_t)l * NP + DM + col], gt = a->b_ada[(size_t)l * NP + 2 * DM + col];
; #pragma unroll
;             for (int ks = 0; ks < 16; ++ks) { const float* b = MODP + (size_t)(ks * 4 + l) * NP; sh += b[col]; sc += b[DM + col]; gt += b[2 * DM + col]; }
;             A1[col] = a->norm_g[l * DM + col] * (1.f + sc); A2[col] = sh; if (bid == 0) GATE[col] = gt;
.LBB0_501:
	v_lshl_add_u64 v[4:5], s[6:7], 0, v[0:1]
	v_add_co_u32_e32 v2, vcc, 0x2000, v4
	v_readlane_b32 s14, v255, 23
	s_nop 0
	v_addc_co_u32_e32 v3, vcc, 0, v5, vcc
	global_load_dword v24, v[4:5], off
	global_load_dword v25, v[2:3], off
	v_lshl_add_u64 v[2:3], s[8:9], 0, v[0:1]
	v_add_co_u32_e32 v8, vcc, 0x8400000, v2
	v_readlane_b32 s15, v255, 24
	s_nop 0
	v_addc_co_u32_e32 v9, vcc, 0, v3, vcc
	v_add_co_u32_e32 v10, vcc, 0x8402000, v2
	s_nop 1
	v_addc_co_u32_e32 v11, vcc, 0, v3, vcc
	v_add_co_u32_e32 v12, vcc, 0x8418000, v2
	s_nop 1
	v_addc_co_u32_e32 v13, vcc, 0, v3, vcc
	v_add_co_u32_e32 v14, vcc, 0x841a000, v2
	s_nop 1
	v_addc_co_u32_e32 v15, vcc, 0, v3, vcc
	v_add_co_u32_e32 v16, vcc, 0x8430000, v2
	s_nop 1
	v_addc_co_u32_e32 v17, vcc, 0, v3, vcc
	v_add_co_u32_e32 v18, vcc, 0x8432000, v2
	s_nop 1
	v_addc_co_u32_e32 v19, vcc, 0, v3, vcc
	v_add_co_u32_e32 v20, vcc, 0x8448000, v2
	s_nop 1
	v_addc_co_u32_e32 v21, vcc, 0, v3, vcc
	v_add_co_u32_e32 v22, vcc, 0x844a000, v2
	s_nop 1
	v_addc_co_u32_e32 v23, vcc, 0, v3, vcc
	global_load_dword v26, v[8:9], off
	global_load_dword v27, v[10:11], off
	global_load_dword v28, v[12:13], off
	global_load_dword v29, v[14:15], off
	global_load_dword v30, v[16:17], off
	global_load_dword v31, v[18:19], off
	global_load_dword v32, v[20:21], off
	global_load_dword v33, v[22:23], off
	v_add_co_u32_e32 v8, vcc, 0x8460000, v2
	s_nop 1
	v_addc_co_u32_e32 v9, vcc, 0, v3, vcc
	v_add_co_u32_e32 v10, vcc, 0x8462000, v2
	s_nop 1
	v_addc_co_u32_e32 v11, vcc, 0, v3, vcc
	v_add_co_u32_e32 v12, vcc, 0x8478000, v2
	s_nop 1
	v_addc_co_u32_e32 v13, vcc, 0, v3, vcc
	v_add_co_u32_e32 v14, vcc, 0x847a000, v2
	s_nop 1
	v_addc_co_u32_e32 v15, vcc, 0, v3, vcc
	v_add_co_u32_e32 v16, vcc, 0x8490000, v2
	s_nop 1
	v_addc_co_u32_e32 v17, vcc, 0, v3, vcc
	v_add_co_u32_e32 v18, vcc, 0x8492000, v2
	s_nop 1
	v_addc_co_u32_e32 v19, vcc, 0, v3, vcc
	v_add_co_u32_e32 v20, vcc, 0x84a8000, v2
	s_nop 1
	v_addc_co_u32_e32 v21, vcc, 0, v3, vcc
	v_add_co_u32_e32 v22, vcc, 0x84aa000, v2
	s_nop 1
	v_addc_co_u32_e32 v23, vcc, 0, v3, vcc
	global_load_dword v34, v[8:9], off
	global_load_dword v35, v[10:11], off
	global_load_dword v36, v[12:13], off
	global_load_dword v37, v[14:15], off
	global_load_dword v38, v[16:17], off
	global_load_dword v39, v[18:19], off
	global_load_dword v40, v[20:21], off
	global_load_dword v41, v[22:23], off
	v_add_co_u32_e32 v8, vcc, 0x84c0000, v2
	s_nop 1
	v_addc_co_u32_e32 v9, vcc, 0, v3, vcc
	v_add_co_u32_e32 v10, vcc, 0x84c2000, v2
	s_nop 1
	v_addc_co_u32_e32 v11, vcc, 0, v3, vcc
	v_add_co_u32_e32 v12, vcc, 0x84d8000, v2
	s_nop 1
	v_addc_co_u32_e32 v13, vcc, 0, v3, vcc
	v_add_co_u32_e32 v14, vcc, 0x84da000, v2
	s_nop 1
	v_addc_co_u32_e32 v15, vcc, 0, v3, vcc
	v_add_co_u32_e32 v16, vcc, 0x84f0000, v2
	s_nop 1
	v_addc_co_u32_e32 v17, vcc, 0, v3, vcc
	v_add_co_u32_e32 v18, vcc, 0x84f2000, v2
	s_nop 1
	v_addc_co_u32_e32 v19, vcc, 0, v3, vcc
	v_add_co_u32_e32 v20, vcc, 0x8508000, v2
	s_nop 1
	v_addc_co_u32_e32 v21, vcc, 0, v3, vcc
	v_add_co_u32_e32 v22, vcc, 0x850a000, v2
	s_nop 1
	v_addc_co_u32_e32 v23, vcc, 0, v3, vcc
	global_load_dword v42, v[8:9], off
	global_load_dword v43, v[10:11], off
	global_load_dword v44, v[12:13], off
	global_load_dword v45, v[14:15], off
	global_load_dword v46, v[16:17], off
	global_load_dword v47, v[18:19], off
	global_load_dword v48, v[20:21], off
	global_load_dword v49, v[22:23], off
	v_add_co_u32_e32 v8, vcc, 0x8520000, v2
	s_nop 1
	v_addc_co_u32_e32 v9, vcc, 0, v3, vcc
	v_add_co_u32_e32 v10, vcc, 0x8522000, v2
	s_nop 1
	v_addc_co_u32_e32 v11, vcc, 0, v3, vcc
	v_add_co_u32_e32 v12, vcc, 0x8538000, v2
	s_nop 1
	v_addc_co_u32_e32 v13, vcc, 0, v3, vcc
	v_add_co_u32_e32 v14, vcc, 0x853a000, v2
	s_nop 1
	v_addc_co_u32_e32 v15, vcc, 0, v3, vcc
	v_add_co_u32_e32 v16, vcc, 0x8550000, v2
	s_nop 1
	v_addc_co_u32_e32 v17, vcc, 0, v3, vcc
	v_add_co_u32_e32 v18, vcc, 0x8552000, v2
	s_nop 1
	v_addc_co_u32_e32 v19, vcc, 0, v3, vcc
	v_add_co_u32_e32 v20, vcc, 0x8568000, v2
	s_nop 1
	v_addc_co_u32_e32 v21, vcc, 0, v3, vcc
	v_add_co_u32_e32 v22, vcc, 0x856a000, v2
	s_nop 1
	v_addc_co_u32_e32 v23, vcc, 0, v3, vcc
	s_load_dwordx2 s[14:15], s[14:15], 0x10
	global_load_dword v50, v[8:9], off
	s_nop 0
	global_load_dword v10, v[10:11], off
	s_nop 0
	global_load_dword v11, v[12:13], off
	s_nop 0
	global_load_dword v12, v[14:15], off
	global_load_dword v13, v[16:17], off
	s_nop 0
	global_load_dword v14, v[18:19], off
	global_load_dword v15, v[20:21], off
	global_load_dword v16, v[22:23], off
	v_add_u32_e32 v8, s13, v7
	v_ashrrev_i32_e32 v9, 31, v8
	s_waitcnt lgkmcnt(0)
	v_lshl_add_u64 v[8:9], v[8:9], 2, s[14:15]
	global_load_dword v8, v[8:9], off
	s_waitcnt vmcnt(1)
	v_add_f32_e32 v17, v25, v27
	v_add_f32_e32 v17, v17, v29
	v_add_f32_e32 v9, v24, v26
	v_add_f32_e32 v17, v17, v31
	v_add_f32_e32 v9, v9, v28
	v_add_f32_e32 v17, v17, v33
	v_add_f32_e32 v9, v9, v30
	v_add_f32_e32 v17, v17, v35
	v_add_f32_e32 v9, v9, v32
	v_add_f32_e32 v17, v17, v37
	v_add_f32_e32 v9, v9, v34
	v_add_f32_e32 v17, v17, v39
	v_add_f32_e32 v9, v9, v36
	v_add_f32_e32 v17, v17, v41
	v_add_f32_e32 v9, v9, v38
	v_add_f32_e32 v9, v9, v40
	s_andn2_b64 vcc, exec, s[4:5]
	v_add_f32_e32 v9, v9, v42
	v_add_f32_e32 v17, v17, v43
	v_add_f32_e32 v9, v9, v44
	v_add_f32_e32 v17, v17, v45
	v_add_f32_e32 v9, v9, v46
	v_add_f32_e32 v17, v17, v47
	v_add_f32_e32 v9, v9, v48
	v_add_f32_e32 v17, v17, v49
	v_add_f32_e32 v9, v9, v50
	v_add_f32_e32 v10, v17, v10
	v_add_f32_e32 v9, v9, v11
	v_add_f32_e32 v10, v10, v12
	v_add_f32_e32 v9, v9, v13
	v_add_f32_e32 v10, v10, v14
	v_add_f32_e32 v9, v9, v15
	v_add_f32_e32 v10, v10, v16
	v_add_f32_e32 v10, 1.0, v10
	s_waitcnt vmcnt(0)
	v_mul_f32_e32 v8, v10, v8
	ds_write2st64_b32 v6, v8, v9 offset1:32
	s_cbranch_vccnz .LBB0_500
; __device__ __forceinline__ void norm_phase(ArgP a, LAS unsigned char* lds, int l, bool final_, const int tid, const int bid) {
;     ...
;             float sh = a->b_ada[(size_t)l * NP + col], sc = a->b_ada[(size_t)l * NP + DM + col], gt = a->b_ada[(size_t)l * NP + 2 * DM + col];
; #pragma unroll
;             for (int ks = 0; ks < 16; ++ks) { const float* b = MODP + (size_t)(ks * 4 + l) * NP; sh += b[col]; sc += b[DM + col]; gt += b[2 * DM + col]; }
;             A1[col] = a->norm_g[l * DM + col] * (1.f + sc); A2[col] = sh; if (bid == 0) GATE[col] = gt;
	v_add_co_u32_e32 v4, vcc, 0x4000, v4
	s_nop 1
	v_addc_co_u32_e32 v5, vcc, 0, v5, vcc
	global_load_dword v22, v[4:5], off
	v_add_co_u32_e32 v4, vcc, 0x8404000, v2
	s_nop 1
	v_addc_co_u32_e32 v5, vcc, 0, v3, vcc
	v_add_co_u32_e32 v8, vcc, 0x841c000, v2
	s_nop 1
	v_addc_co_u32_e32 v9, vcc, 0, v3, vcc
	v_add_co_u32_e32 v10, vcc, 0x8434000, v2
	s_nop 1
	v_addc_co_u32_e32 v11, vcc, 0, v3, vcc
	v_add_co_u32_e32 v12, vcc, 0x844c000, v2
	s_nop 1
	v_addc_co_u32_e32 v13, vcc, 0, v3, vcc
	v_add_co_u32_e32 v14, vcc, 0x8464000, v2
	s_nop 1
	v_addc_co_u32_e32 v15, vcc, 0, v3, vcc
	v_add_co_u32_e32 v16, vcc, 0x847c000, v2
	s_nop 1
	v_addc_co_u32_e32 v17, vcc, 0, v3, vcc
	v_add_co_u32_e32 v18, vcc, 0x8494000, v2
	s_nop 1
	v_addc_co_u32_e32 v19, vcc, 0, v3, vcc
	v_add_co_u32_e32 v20, vcc, 0x84ac000, v2
	s_nop 1
	v_addc_co_u32_e32 v21, vcc, 0, v3, vcc
	global_load_dword v23, v[4:5], off
	global_load_dword v24, v[8:9], off
	global_load_dword v25, v[10:11], off
	global_load_dword v26, v[12:13], off
	global_load_dword v27, v[14:15], off
	global_load_dword v28, v[16:17], off
	global_load_dword v29, v[18:19], off
	s_nop 0
	global_load_dword v20, v[20:21], off
	v_add_co_u32_e32 v4, vcc, 0x84c4000, v2
	s_nop 1
	v_addc_co_u32_e32 v5, vcc, 0, v3, vcc
	v_add_co_u32_e32 v8, vcc, 0x84dc000, v2
	s_nop 1
	v_addc_co_u32_e32 v9, vcc, 0, v3, vcc
	v_add_co_u32_e32 v10, vcc, 0x84f4000, v2
	s_nop 1
	v_addc_co_u32_e32 v11, vcc, 0, v3, vcc
	v_add_co_u32_e32 v12, vcc, 0x850c000, v2
	s_nop 1
	v_addc_co_u32_e32 v13, vcc, 0, v3, vcc
	v_add_co_u32_e32 v14, vcc, 0x8524000, v2
	s_nop 1
	v_addc_co_u32_e32 v15, vcc, 0, v3, vcc
	v_add_co_u32_e32 v16, vcc, 0x853c000, v2
	s_nop 1
	v_addc_co_u32_e32 v17, vcc, 0, v3, vcc
	v_add_co_u32_e32 v18, vcc, 0x8554000, v2
	s_nop 1
	v_addc_co_u32_e32 v19, vcc, 0, v3, vcc
	v_add_co_u32_e32 v2, vcc, 0x856c000, v2
	s_nop 1
	v_addc_co_u32_e32 v3, vcc, 0, v3, vcc
	global_load_dword v4, v[4:5], off
	s_nop 0
	global_load_dword v5, v[8:9], off
	s_nop 0
	global_load_dword v8, v[10:11], off
	global_load_dword v9, v[12:13], off
	s_nop 0
	global_load_dword v10, v[14:15], off
	global_load_dword v11, v[16:17], off
	global_load_dword v12, v[18:19], off
	s_nop 0
	global_load_dword v2, v[2:3], off
	s_waitcnt vmcnt(15)
	v_add_f32_e32 v3, v22, v23
	s_waitcnt vmcnt(14)
	v_add_f32_e32 v3, v3, v24
	s_waitcnt vmcnt(13)
	v_add_f32_e32 v3, v3, v25
	s_waitcnt vmcnt(12)
	v_add_f32_e32 v3, v3, v26
	s_waitcnt vmcnt(11)
	v_add_f32_e32 v3, v3, v27
	s_waitcnt vmcnt(10)
	v_add_f32_e32 v3, v3, v28
	s_waitcnt vmcnt(9)
	v_add_f32_e32 v3, v3, v29
	s_waitcnt vmcnt(8)
	v_add_f32_e32 v3, v3, v20
	s_waitcnt vmcnt(7)
	v_add_f32_e32 v3, v3, v4
	s_waitcnt vmcnt(6)
	v_add_f32_e32 v3, v3, v5
	s_waitcnt vmcnt(5)
	v_add_f32_e32 v3, v3, v8
	s_waitcnt vmcnt(4)
	v_add_f32_e32 v3, v3, v9
	s_waitcnt vmcnt(3)
	v_add_f32_e32 v3, v3, v10
	s_waitcnt vmcnt(2)
	v_add_f32_e32 v3, v3, v11
	s_waitcnt vmcnt(1)
	v_add_f32_e32 v3, v3, v12
	s_waitcnt vmcnt(0)
	v_add_f32_e32 v4, v3, v2
	v_lshl_add_u64 v[2:3], s[2:3], 0, v[0:1]
	global_store_dword v[2:3], v4, off
	s_branch .LBB0_500
